# in-proj tile scheduler: 8x4 XCD patches for token rows cols 0-31, 16x2 for cols 32-33 and context rows (was 16x2 everywhere)
# baseline (speedup 1.0000x reference)
.LBB0_590:
	s_andn2_b64 vcc, exec, s[54:55]
	s_cbranch_vccnz .LBB0_594
	s_and_b32 s44, s37, 7
	s_add_i32 s39, s30, s44
	s_cmpk_gt_u32 s39, 0x98
	s_mov_b64 s[20:21], 0
	s_cbranch_scc1 .LBB0_593
	s_lshr_b32 s20, s37, 3
	s_cmpk_lt_u32 s39, 0x80
	s_cbranch_scc0 .Lsp_r2_ipf0
	s_and_b32 s34, s39, -8
	s_lshr_b32 s21, s20, 2
	s_add_i32 s34, s34, s21
	s_and_b32 s35, s39, 7
	s_lshl_b32 s35, s35, 2
	s_and_b32 s21, s20, 3
	s_add_i32 s35, s35, s21
	s_branch .Lsp_dn_ipf0
.Lsp_r2_ipf0:
	s_lshr_b32 s21, s20, 1
	s_and_b32 s20, s20, 1
	s_cmpk_lt_u32 s39, 0x88
	s_cbranch_scc0 .Lsp_r3_ipf0
	s_add_i32 s34, s39, 0xffffff80
	s_lshl_b32 s34, s34, 4
	s_add_i32 s34, s34, s21
	s_or_b32 s35, s20, 32
	s_branch .Lsp_dn_ipf0
.Lsp_r3_ipf0:
	s_add_i32 s34, s21, 0x80
	s_add_i32 s35, s39, 0xffffff78
	s_lshl_b32 s35, s35, 1
	s_add_i32 s35, s35, s20
.Lsp_dn_ipf0:
	s_mov_b64 s[20:21], -1
.LBB0_593:
	s_mov_b32 s44, s34
	s_mov_b32 s52, s35

.LBB0_627:
	s_andn2_b64 vcc, exec, s[66:67]
	s_cbranch_vccnz .LBB0_631
	s_and_b32 s62, s68, 7
	s_add_i32 s39, s30, s62
	s_cmpk_gt_u32 s39, 0x98
	s_mov_b64 s[20:21], 0
	s_cbranch_scc1 .LBB0_630
	s_lshr_b32 s20, s68, 3
	s_cmpk_lt_u32 s39, 0x80
	s_cbranch_scc0 .Lsp_r2_ipl0
	s_and_b32 s37, s39, -8
	s_lshr_b32 s21, s20, 2
	s_add_i32 s37, s37, s21
	s_and_b32 s65, s39, 7
	s_lshl_b32 s65, s65, 2
	s_and_b32 s21, s20, 3
	s_add_i32 s65, s65, s21
	s_branch .Lsp_dn_ipl0
.Lsp_r2_ipl0:
	s_lshr_b32 s21, s20, 1
	s_and_b32 s20, s20, 1
	s_cmpk_lt_u32 s39, 0x88
	s_cbranch_scc0 .Lsp_r3_ipl0
	s_add_i32 s37, s39, 0xffffff80
	s_lshl_b32 s37, s37, 4
	s_add_i32 s37, s37, s21
	s_or_b32 s65, s20, 32
	s_branch .Lsp_dn_ipl0
.Lsp_r3_ipl0:
	s_add_i32 s37, s21, 0x80
	s_add_i32 s65, s39, 0xffffff78
	s_lshl_b32 s65, s65, 1
	s_add_i32 s65, s65, s20
.Lsp_dn_ipl0:
	s_mov_b64 s[20:21], -1
.LBB0_630:
	s_mov_b32 s62, s37
	s_mov_b32 s64, s65

.Lsp_dn_ipf1:
	s_mov_b64 s[20:21], -1
.LBB0_1139:
	s_mov_b32 s44, s34
	s_mov_b32 s52, s35

.Lsp_dn_ipl1:
	s_mov_b64 s[20:21], -1
.LBB0_1165:
	s_mov_b32 s62, s37
	s_mov_b32 s64, s65
